# gdn_prep conv+silu: tap reads batched 16 at a time one batch ahead of the silu maths; all 12 conv weights loaded once per item
# speedup vs baseline: 1.0132x; 1.0132x over previous
; DI float bf2f(bf16_t v) { return __uint_as_float(((unsigned)v) << 16); }
; DI float siluf_(float x) { return x / (1.f + __expf(-x)); }
; DI void phase_gdn_prep(const Params& p, int l, char* smem) {
;     ...
; #pragma unroll
;             for (int part = 0; part < 3; ++part) {
; #pragma unroll
;                 for (int k = 0; k < 3; ++k) { const int c = tid + 256 * k; if (c < 67 * 8) *(u32x4*)(sraw + c * 8) = raw[part * 3 + k]; }
;                 __syncthreads();
;                 const int col = part * 384 + h * 64 + ch;
;                 const float w0 = cw[col], w1 = cw[1152 + col], w2 = cw[2 * 1152 + col], w3 = cw[3 * 1152 + col];
;                 float* dst = part == 0 ? sq : (part == 1 ? sk : sv);
; #pragma unroll
;                 for (int i = 0; i < 16; ++i) {
;                     const int t = tq + 4 * i;
;                     const float x0 = bf2f(sraw[(t + 0) * 64 + ch]), x1 = bf2f(sraw[(t + 1) * 64 + ch]);
;                     const float x2 = bf2f(sraw[(t + 2) * 64 + ch]), x3 = bf2f(sraw[(t + 3) * 64 + ch]);
;                     const float a = x0 * w0 + x1 * w1 + x2 * w2 + x3 * w3;
;                     dst[t * 65 + ch] = siluf_(a);
;                 }
;                 __syncthreads();
.LBB0_268:
	s_or_b64 exec, exec, s[4:5]
	s_ashr_i32 s4, s86, 8
	s_mul_hi_i32 s5, s4, 0x2aaaaaab
	s_lshr_b32 s6, s5, 31
	s_add_i32 s5, s5, s6
	s_mul_i32 s5, s5, 6
	s_sub_i32 s6, s4, s5
	s_waitcnt vmcnt(4)
	v_lshl_or_b32 v24, s6, 6, v62
	v_ashrrev_i32_e32 v25, 31, v24
	v_lshl_add_u64 v[24:25], v[24:25], 2, s[40:41]
	v_add_co_u32_e32 v28, vcc, s35, v24
	s_waitcnt lgkmcnt(0)
	s_nop 0
	v_addc_co_u32_e32 v29, vcc, 0, v25, vcc
	s_barrier
	global_load_dword v37, v[24:25], off
	global_load_dword v58, v[24:25], off offset:1536
	global_load_dword v76, v[24:25], off offset:3072
	v_add_co_u32_e32 v208, vcc, 0x1200, v24
	s_nop 1
	v_addc_co_u32_e32 v209, vcc, 0, v25, vcc
	global_load_dword v38, v[208:209], off
	global_load_dword v59, v[208:209], off offset:1536
	global_load_dword v185, v[208:209], off offset:3072
	v_add_co_u32_e32 v208, vcc, 0x1200, v208
	s_nop 1
	v_addc_co_u32_e32 v209, vcc, 0, v209, vcc
	global_load_dword v39, v[208:209], off
	global_load_dword v60, v[208:209], off offset:1536
	global_load_dword v186, v[208:209], off offset:3072
	v_add_co_u32_e32 v208, vcc, 0x1200, v208
	s_nop 1
	v_addc_co_u32_e32 v209, vcc, 0, v209, vcc
	global_load_dword v54, v[208:209], off
	global_load_dword v61, v[208:209], off offset:1536
	global_load_dword v187, v[208:209], off offset:3072
	ds_read_u16 v191, v78 offset:49920
	ds_read_u16 v192, v78 offset:50048
	ds_read_u16 v193, v78 offset:50176
	ds_read_u16 v194, v78 offset:50304
	ds_read_u16 v195, v78 offset:50432
	ds_read_u16 v196, v78 offset:50560
	ds_read_u16 v197, v78 offset:50688
	ds_read_u16 v198, v78 offset:50816
	ds_read_u16 v199, v78 offset:50944
	ds_read_u16 v200, v78 offset:51072
	ds_read_u16 v201, v78 offset:51200
	ds_read_u16 v202, v78 offset:51328
	ds_read_u16 v203, v78 offset:51456
	ds_read_u16 v204, v78 offset:51584
	ds_read_u16 v205, v78 offset:51712
	ds_read_u16 v206, v78 offset:51840
	s_waitcnt vmcnt(0)
	s_waitcnt lgkmcnt(0)
	v_lshlrev_b32_e32 v191, 16, v191
	v_lshlrev_b32_e32 v192, 16, v192
	v_lshlrev_b32_e32 v193, 16, v193
	v_lshlrev_b32_e32 v194, 16, v194
	v_mul_f32_e32 v230, v38, v192
	v_fmac_f32_e32 v230, v37, v191
	v_fmac_f32_e32 v230, v39, v193
	v_fmac_f32_e32 v230, v54, v194
	v_lshlrev_b32_e32 v195, 16, v195
	v_lshlrev_b32_e32 v196, 16, v196
	v_lshlrev_b32_e32 v197, 16, v197
	v_lshlrev_b32_e32 v198, 16, v198
	v_mul_f32_e32 v231, v38, v196
	v_fmac_f32_e32 v231, v37, v195
	v_fmac_f32_e32 v231, v39, v197
	v_fmac_f32_e32 v231, v54, v198
	v_lshlrev_b32_e32 v199, 16, v199
	v_lshlrev_b32_e32 v200, 16, v200
	v_lshlrev_b32_e32 v201, 16, v201
	v_lshlrev_b32_e32 v202, 16, v202
	v_mul_f32_e32 v232, v38, v200
	v_fmac_f32_e32 v232, v37, v199
	v_fmac_f32_e32 v232, v39, v201
	v_fmac_f32_e32 v232, v54, v202
	v_lshlrev_b32_e32 v203, 16, v203
	v_lshlrev_b32_e32 v204, 16, v204
	v_lshlrev_b32_e32 v205, 16, v205
	v_lshlrev_b32_e32 v206, 16, v206
	v_mul_f32_e32 v233, v38, v204
	v_fmac_f32_e32 v233, v37, v203
	v_fmac_f32_e32 v233, v39, v205
	v_fmac_f32_e32 v233, v54, v206
	ds_read_u16 v191, v78 offset:51968
	ds_read_u16 v192, v78 offset:52096
	ds_read_u16 v193, v78 offset:52224
	ds_read_u16 v194, v78 offset:52352
	ds_read_u16 v195, v78 offset:52480
	ds_read_u16 v196, v78 offset:52608
	ds_read_u16 v197, v78 offset:52736
	ds_read_u16 v198, v78 offset:52864
	ds_read_u16 v199, v78 offset:52992
	ds_read_u16 v200, v78 offset:53120
	ds_read_u16 v201, v78 offset:53248
	ds_read_u16 v202, v78 offset:53376
	ds_read_u16 v203, v78 offset:53504
	ds_read_u16 v204, v78 offset:53632
	ds_read_u16 v205, v78 offset:53760
	ds_read_u16 v206, v78 offset:53888
	v_mul_f32_e32 v234, 0xbfb8aa3b, v230
	v_exp_f32_e32 v234, v234
	s_nop 0
	v_add_f32_e32 v234, 1.0, v234
	v_div_scale_f32 v235, s[4:5], v234, v234, v230
	v_rcp_f32_e32 v236, v235
	s_nop 0
	v_fma_f32 v237, -v235, v236, 1.0
	v_fmac_f32_e32 v236, v237, v236
	v_div_scale_f32 v237, vcc, v230, v234, v230
	v_mul_f32_e32 v238, v237, v236
	v_fma_f32 v239, -v235, v238, v237
	v_fmac_f32_e32 v238, v239, v236
	v_fma_f32 v235, -v235, v238, v237
	v_div_fmas_f32 v235, v235, v236, v238
	v_div_fixup_f32 v234, v235, v234, v230
	ds_write_b32 v173, v234
	v_mul_f32_e32 v234, 0xbfb8aa3b, v231
	v_exp_f32_e32 v234, v234
	s_nop 0
	v_add_f32_e32 v234, 1.0, v234
	v_div_scale_f32 v235, s[4:5], v234, v234, v231
	v_rcp_f32_e32 v236, v235
	s_nop 0
	v_fma_f32 v237, -v235, v236, 1.0
	v_fmac_f32_e32 v236, v237, v236
	v_div_scale_f32 v237, vcc, v231, v234, v231
	v_mul_f32_e32 v238, v237, v236
	v_fma_f32 v239, -v235, v238, v237
	v_fmac_f32_e32 v238, v239, v236
	v_fma_f32 v235, -v235, v238, v237
	v_div_fmas_f32 v235, v235, v236, v238
	v_div_fixup_f32 v234, v235, v234, v231
	ds_write_b32 v173, v234 offset:1040
	v_mul_f32_e32 v234, 0xbfb8aa3b, v232
	v_exp_f32_e32 v234, v234
	s_nop 0
	v_add_f32_e32 v234, 1.0, v234
	v_div_scale_f32 v235, s[4:5], v234, v234, v232
	v_rcp_f32_e32 v236, v235
	s_nop 0
	v_fma_f32 v237, -v235, v236, 1.0
	v_fmac_f32_e32 v236, v237, v236
	v_div_scale_f32 v237, vcc, v232, v234, v232
	v_mul_f32_e32 v238, v237, v236
	v_fma_f32 v239, -v235, v238, v237
	v_fmac_f32_e32 v238, v239, v236
	v_fma_f32 v235, -v235, v238, v237
	v_div_fmas_f32 v235, v235, v236, v238
	v_div_fixup_f32 v234, v235, v234, v232
	ds_write_b32 v173, v234 offset:2080
	v_mul_f32_e32 v234, 0xbfb8aa3b, v233
	v_exp_f32_e32 v234, v234
	s_nop 0
	v_add_f32_e32 v234, 1.0, v234
	v_div_scale_f32 v235, s[4:5], v234, v234, v233
	v_rcp_f32_e32 v236, v235
	s_nop 0
	v_fma_f32 v237, -v235, v236, 1.0
	v_fmac_f32_e32 v236, v237, v236
	v_div_scale_f32 v237, vcc, v233, v234, v233
	v_mul_f32_e32 v238, v237, v236
	v_fma_f32 v239, -v235, v238, v237
	v_fmac_f32_e32 v238, v239, v236
	v_fma_f32 v235, -v235, v238, v237
	v_div_fmas_f32 v235, v235, v236, v238
	v_div_fixup_f32 v234, v235, v234, v233
	ds_write_b32 v173, v234 offset:3120
	s_waitcnt lgkmcnt(0)
; DI float bf2f(bf16_t v) { return __uint_as_float(((unsigned)v) << 16); }
; DI float siluf_(float x) { return x / (1.f + __expf(-x)); }
; DI void phase_gdn_prep(const Params& p, int l, char* smem) {
;     ...
; #pragma unroll
;                 for (int i = 0; i < 16; ++i) {
;                     const int t = tq + 4 * i;
;                     const float x0 = bf2f(sraw[(t + 0) * 64 + ch]), x1 = bf2f(sraw[(t + 1) * 64 + ch]);
;                     const float x2 = bf2f(sraw[(t + 2) * 64 + ch]), x3 = bf2f(sraw[(t + 3) * 64 + ch]);
;                     const float a = x0 * w0 + x1 * w1 + x2 * w2 + x3 * w3;
;                     dst[t * 65 + ch] = siluf_(a);
;                 }
;                 __syncthreads();
	v_lshlrev_b32_e32 v191, 16, v191
	v_lshlrev_b32_e32 v192, 16, v192
	v_lshlrev_b32_e32 v193, 16, v193
	v_lshlrev_b32_e32 v194, 16, v194
	v_mul_f32_e32 v230, v38, v192
	v_fmac_f32_e32 v230, v37, v191
	v_fmac_f32_e32 v230, v39, v193
	v_fmac_f32_e32 v230, v54, v194
	v_lshlrev_b32_e32 v195, 16, v195
	v_lshlrev_b32_e32 v196, 16, v196
	v_lshlrev_b32_e32 v197, 16, v197
	v_lshlrev_b32_e32 v198, 16, v198
	v_mul_f32_e32 v231, v38, v196
	v_fmac_f32_e32 v231, v37, v195
	v_fmac_f32_e32 v231, v39, v197
	v_fmac_f32_e32 v231, v54, v198
	v_lshlrev_b32_e32 v199, 16, v199
	v_lshlrev_b32_e32 v200, 16, v200
	v_lshlrev_b32_e32 v201, 16, v201
	v_lshlrev_b32_e32 v202, 16, v202
	v_mul_f32_e32 v232, v38, v200
	v_fmac_f32_e32 v232, v37, v199
	v_fmac_f32_e32 v232, v39, v201
	v_fmac_f32_e32 v232, v54, v202
	v_lshlrev_b32_e32 v203, 16, v203
	v_lshlrev_b32_e32 v204, 16, v204
	v_lshlrev_b32_e32 v205, 16, v205
	v_lshlrev_b32_e32 v206, 16, v206
	v_mul_f32_e32 v233, v38, v204
	v_fmac_f32_e32 v233, v37, v203
	v_fmac_f32_e32 v233, v39, v205
	v_fmac_f32_e32 v233, v54, v206
	ds_read_u16 v191, v78 offset:54016
	ds_read_u16 v192, v78 offset:54144
	ds_read_u16 v193, v78 offset:54272
	ds_read_u16 v194, v78 offset:54400
	ds_read_u16 v195, v78 offset:54528
	ds_read_u16 v196, v78 offset:54656
	ds_read_u16 v197, v78 offset:54784
	ds_read_u16 v198, v78 offset:54912
	ds_read_u16 v199, v78 offset:55040
	ds_read_u16 v200, v78 offset:55168
	ds_read_u16 v201, v78 offset:55296
	ds_read_u16 v202, v78 offset:55424
	ds_read_u16 v203, v78 offset:55552
	ds_read_u16 v204, v78 offset:55680
	ds_read_u16 v205, v78 offset:55808
	ds_read_u16 v206, v78 offset:55936
	v_mul_f32_e32 v234, 0xbfb8aa3b, v230
	v_exp_f32_e32 v234, v234
	s_nop 0
	v_add_f32_e32 v234, 1.0, v234
	v_div_scale_f32 v235, s[4:5], v234, v234, v230
	v_rcp_f32_e32 v236, v235
	s_nop 0
	v_fma_f32 v237, -v235, v236, 1.0
	v_fmac_f32_e32 v236, v237, v236
	v_div_scale_f32 v237, vcc, v230, v234, v230
	v_mul_f32_e32 v238, v237, v236
	v_fma_f32 v239, -v235, v238, v237
	v_fmac_f32_e32 v238, v239, v236
	v_fma_f32 v235, -v235, v238, v237
	v_div_fmas_f32 v235, v235, v236, v238
	v_div_fixup_f32 v234, v235, v234, v230
	ds_write_b32 v173, v234 offset:4160
	v_mul_f32_e32 v234, 0xbfb8aa3b, v231
	v_exp_f32_e32 v234, v234
	s_nop 0
	v_add_f32_e32 v234, 1.0, v234
	v_div_scale_f32 v235, s[4:5], v234, v234, v231
	v_rcp_f32_e32 v236, v235
	s_nop 0
	v_fma_f32 v237, -v235, v236, 1.0
	v_fmac_f32_e32 v236, v237, v236
	v_div_scale_f32 v237, vcc, v231, v234, v231
	v_mul_f32_e32 v238, v237, v236
	v_fma_f32 v239, -v235, v238, v237
	v_fmac_f32_e32 v238, v239, v236
	v_fma_f32 v235, -v235, v238, v237
	v_div_fmas_f32 v235, v235, v236, v238
	v_div_fixup_f32 v234, v235, v234, v231
	ds_write_b32 v173, v234 offset:5200
	v_mul_f32_e32 v234, 0xbfb8aa3b, v232
	v_exp_f32_e32 v234, v234
	s_nop 0
	v_add_f32_e32 v234, 1.0, v234
	v_div_scale_f32 v235, s[4:5], v234, v234, v232
	v_rcp_f32_e32 v236, v235
	s_nop 0
	v_fma_f32 v237, -v235, v236, 1.0
	v_fmac_f32_e32 v236, v237, v236
	v_div_scale_f32 v237, vcc, v232, v234, v232
	v_mul_f32_e32 v238, v237, v236
	v_fma_f32 v239, -v235, v238, v237
	v_fmac_f32_e32 v238, v239, v236
	v_fma_f32 v235, -v235, v238, v237
	v_div_fmas_f32 v235, v235, v236, v238
	v_div_fixup_f32 v234, v235, v234, v232
	ds_write_b32 v173, v234 offset:6240
	v_mul_f32_e32 v234, 0xbfb8aa3b, v233
	v_exp_f32_e32 v234, v234
	s_nop 0
	v_add_f32_e32 v234, 1.0, v234
	v_div_scale_f32 v235, s[4:5], v234, v234, v233
	v_rcp_f32_e32 v236, v235
	s_nop 0
	v_fma_f32 v237, -v235, v236, 1.0
	v_fmac_f32_e32 v236, v237, v236
	v_div_scale_f32 v237, vcc, v233, v234, v233
	v_mul_f32_e32 v238, v237, v236
	v_fma_f32 v239, -v235, v238, v237
	v_fmac_f32_e32 v238, v239, v236
	v_fma_f32 v235, -v235, v238, v237
	v_div_fmas_f32 v235, v235, v236, v238
	v_div_fixup_f32 v234, v235, v234, v233
	ds_write_b32 v173, v234 offset:7280
	s_waitcnt lgkmcnt(0)
	v_lshlrev_b32_e32 v191, 16, v191
	v_lshlrev_b32_e32 v192, 16, v192
	v_lshlrev_b32_e32 v193, 16, v193
	v_lshlrev_b32_e32 v194, 16, v194
	v_mul_f32_e32 v230, v38, v192
	v_fmac_f32_e32 v230, v37, v191
	v_fmac_f32_e32 v230, v39, v193
	v_fmac_f32_e32 v230, v54, v194
	v_lshlrev_b32_e32 v195, 16, v195
	v_lshlrev_b32_e32 v196, 16, v196
	v_lshlrev_b32_e32 v197, 16, v197
	v_lshlrev_b32_e32 v198, 16, v198
	v_mul_f32_e32 v231, v38, v196
	v_fmac_f32_e32 v231, v37, v195
	v_fmac_f32_e32 v231, v39, v197
	v_fmac_f32_e32 v231, v54, v198
	v_lshlrev_b32_e32 v199, 16, v199
	v_lshlrev_b32_e32 v200, 16, v200
	v_lshlrev_b32_e32 v201, 16, v201
	v_lshlrev_b32_e32 v202, 16, v202
	v_mul_f32_e32 v232, v38, v200
	v_fmac_f32_e32 v232, v37, v199
	v_fmac_f32_e32 v232, v39, v201
	v_fmac_f32_e32 v232, v54, v202
	v_lshlrev_b32_e32 v203, 16, v203
	v_lshlrev_b32_e32 v204, 16, v204
	v_lshlrev_b32_e32 v205, 16, v205
	v_lshlrev_b32_e32 v206, 16, v206
	v_mul_f32_e32 v233, v38, v204
	v_fmac_f32_e32 v233, v37, v203
	v_fmac_f32_e32 v233, v39, v205
	v_fmac_f32_e32 v233, v54, v206
	ds_read_u16 v191, v78 offset:56064
	ds_read_u16 v192, v78 offset:56192
	ds_read_u16 v193, v78 offset:56320
	ds_read_u16 v194, v78 offset:56448
	ds_read_u16 v195, v78 offset:56576
	ds_read_u16 v196, v78 offset:56704
	ds_read_u16 v197, v78 offset:56832
	ds_read_u16 v198, v78 offset:56960
	ds_read_u16 v199, v78 offset:57088
	ds_read_u16 v200, v78 offset:57216
	ds_read_u16 v201, v78 offset:57344
	ds_read_u16 v202, v78 offset:57472
	ds_read_u16 v203, v78 offset:57600
	ds_read_u16 v204, v78 offset:57728
	ds_read_u16 v205, v78 offset:57856
	ds_read_u16 v206, v78 offset:57984
	v_mul_f32_e32 v234, 0xbfb8aa3b, v230
	v_exp_f32_e32 v234, v234
	s_nop 0
	v_add_f32_e32 v234, 1.0, v234
; DI float bf2f(bf16_t v) { return __uint_as_float(((unsigned)v) << 16); }
; DI float siluf_(float x) { return x / (1.f + __expf(-x)); }
; DI void phase_gdn_prep(const Params& p, int l, char* smem) {
;     ...
; #pragma unroll
;                 for (int i = 0; i < 16; ++i) {
;                     const int t = tq + 4 * i;
;                     const float x0 = bf2f(sraw[(t + 0) * 64 + ch]), x1 = bf2f(sraw[(t + 1) * 64 + ch]);
;                     const float x2 = bf2f(sraw[(t + 2) * 64 + ch]), x3 = bf2f(sraw[(t + 3) * 64 + ch]);
;                     const float a = x0 * w0 + x1 * w1 + x2 * w2 + x3 * w3;
;                     dst[t * 65 + ch] = siluf_(a);
;                 }
;                 __syncthreads();
	v_div_scale_f32 v235, s[4:5], v234, v234, v230
	v_rcp_f32_e32 v236, v235
	s_nop 0
	v_fma_f32 v237, -v235, v236, 1.0
	v_fmac_f32_e32 v236, v237, v236
	v_div_scale_f32 v237, vcc, v230, v234, v230
	v_mul_f32_e32 v238, v237, v236
	v_fma_f32 v239, -v235, v238, v237
	v_fmac_f32_e32 v238, v239, v236
	v_fma_f32 v235, -v235, v238, v237
	v_div_fmas_f32 v235, v235, v236, v238
	v_div_fixup_f32 v234, v235, v234, v230
	ds_write_b32 v173, v234 offset:8320
	v_mul_f32_e32 v234, 0xbfb8aa3b, v231
	v_exp_f32_e32 v234, v234
	s_nop 0
	v_add_f32_e32 v234, 1.0, v234
	v_div_scale_f32 v235, s[4:5], v234, v234, v231
	v_rcp_f32_e32 v236, v235
	s_nop 0
	v_fma_f32 v237, -v235, v236, 1.0
	v_fmac_f32_e32 v236, v237, v236
	v_div_scale_f32 v237, vcc, v231, v234, v231
	v_mul_f32_e32 v238, v237, v236
	v_fma_f32 v239, -v235, v238, v237
	v_fmac_f32_e32 v238, v239, v236
	v_fma_f32 v235, -v235, v238, v237
	v_div_fmas_f32 v235, v235, v236, v238
	v_div_fixup_f32 v234, v235, v234, v231
	ds_write_b32 v173, v234 offset:9360
	v_mul_f32_e32 v234, 0xbfb8aa3b, v232
	v_exp_f32_e32 v234, v234
	s_nop 0
	v_add_f32_e32 v234, 1.0, v234
	v_div_scale_f32 v235, s[4:5], v234, v234, v232
	v_rcp_f32_e32 v236, v235
	s_nop 0
	v_fma_f32 v237, -v235, v236, 1.0
	v_fmac_f32_e32 v236, v237, v236
	v_div_scale_f32 v237, vcc, v232, v234, v232
	v_mul_f32_e32 v238, v237, v236
	v_fma_f32 v239, -v235, v238, v237
	v_fmac_f32_e32 v238, v239, v236
	v_fma_f32 v235, -v235, v238, v237
	v_div_fmas_f32 v235, v235, v236, v238
	v_div_fixup_f32 v234, v235, v234, v232
	ds_write_b32 v173, v234 offset:10400
	v_mul_f32_e32 v234, 0xbfb8aa3b, v233
	v_exp_f32_e32 v234, v234
	s_nop 0
	v_add_f32_e32 v234, 1.0, v234
	v_div_scale_f32 v235, s[4:5], v234, v234, v233
	v_rcp_f32_e32 v236, v235
	s_nop 0
	v_fma_f32 v237, -v235, v236, 1.0
	v_fmac_f32_e32 v236, v237, v236
	v_div_scale_f32 v237, vcc, v233, v234, v233
	v_mul_f32_e32 v238, v237, v236
	v_fma_f32 v239, -v235, v238, v237
	v_fmac_f32_e32 v238, v239, v236
	v_fma_f32 v235, -v235, v238, v237
	v_div_fmas_f32 v235, v235, v236, v238
	v_div_fixup_f32 v234, v235, v234, v233
	ds_write_b32 v173, v234 offset:11440
	s_waitcnt lgkmcnt(0)
	v_lshlrev_b32_e32 v191, 16, v191
	v_lshlrev_b32_e32 v192, 16, v192
	v_lshlrev_b32_e32 v193, 16, v193
	v_lshlrev_b32_e32 v194, 16, v194
	v_mul_f32_e32 v230, v38, v192
	v_fmac_f32_e32 v230, v37, v191
	v_fmac_f32_e32 v230, v39, v193
	v_fmac_f32_e32 v230, v54, v194
	v_lshlrev_b32_e32 v195, 16, v195
	v_lshlrev_b32_e32 v196, 16, v196
	v_lshlrev_b32_e32 v197, 16, v197
	v_lshlrev_b32_e32 v198, 16, v198
	v_mul_f32_e32 v231, v38, v196
	v_fmac_f32_e32 v231, v37, v195
	v_fmac_f32_e32 v231, v39, v197
	v_fmac_f32_e32 v231, v54, v198
	v_lshlrev_b32_e32 v199, 16, v199
	v_lshlrev_b32_e32 v200, 16, v200
	v_lshlrev_b32_e32 v201, 16, v201
	v_lshlrev_b32_e32 v202, 16, v202
	v_mul_f32_e32 v232, v38, v200
	v_fmac_f32_e32 v232, v37, v199
	v_fmac_f32_e32 v232, v39, v201
	v_fmac_f32_e32 v232, v54, v202
	v_lshlrev_b32_e32 v203, 16, v203
	v_lshlrev_b32_e32 v204, 16, v204
	v_lshlrev_b32_e32 v205, 16, v205
	v_lshlrev_b32_e32 v206, 16, v206
	v_mul_f32_e32 v233, v38, v204
	v_fmac_f32_e32 v233, v37, v203
	v_fmac_f32_e32 v233, v39, v205
	v_fmac_f32_e32 v233, v54, v206
	v_mul_f32_e32 v234, 0xbfb8aa3b, v230
	v_exp_f32_e32 v234, v234
	s_nop 0
	v_add_f32_e32 v234, 1.0, v234
	v_div_scale_f32 v235, s[4:5], v234, v234, v230
	v_rcp_f32_e32 v236, v235
	s_nop 0
	v_fma_f32 v237, -v235, v236, 1.0
	v_fmac_f32_e32 v236, v237, v236
	v_div_scale_f32 v237, vcc, v230, v234, v230
	v_mul_f32_e32 v238, v237, v236
	v_fma_f32 v239, -v235, v238, v237
	v_fmac_f32_e32 v238, v239, v236
	v_fma_f32 v235, -v235, v238, v237
	v_div_fmas_f32 v235, v235, v236, v238
	v_div_fixup_f32 v234, v235, v234, v230
	ds_write_b32 v173, v234 offset:12480
	v_mul_f32_e32 v234, 0xbfb8aa3b, v231
	v_exp_f32_e32 v234, v234
	s_nop 0
	v_add_f32_e32 v234, 1.0, v234
	v_div_scale_f32 v235, s[4:5], v234, v234, v231
	v_rcp_f32_e32 v236, v235
	s_nop 0
	v_fma_f32 v237, -v235, v236, 1.0
	v_fmac_f32_e32 v236, v237, v236
	v_div_scale_f32 v237, vcc, v231, v234, v231
	v_mul_f32_e32 v238, v237, v236
	v_fma_f32 v239, -v235, v238, v237
	v_fmac_f32_e32 v238, v239, v236
	v_fma_f32 v235, -v235, v238, v237
	v_div_fmas_f32 v235, v235, v236, v238
	v_div_fixup_f32 v234, v235, v234, v231
	ds_write_b32 v173, v234 offset:13520
	v_mul_f32_e32 v234, 0xbfb8aa3b, v232
	v_exp_f32_e32 v234, v234
	s_nop 0
	v_add_f32_e32 v234, 1.0, v234
	v_div_scale_f32 v235, s[4:5], v234, v234, v232
	v_rcp_f32_e32 v236, v235
	s_nop 0
	v_fma_f32 v237, -v235, v236, 1.0
	v_fmac_f32_e32 v236, v237, v236
	v_div_scale_f32 v237, vcc, v232, v234, v232
	v_mul_f32_e32 v238, v237, v236
	v_fma_f32 v239, -v235, v238, v237
	v_fmac_f32_e32 v238, v239, v236
	v_fma_f32 v235, -v235, v238, v237
	v_div_fmas_f32 v235, v235, v236, v238
	v_div_fixup_f32 v234, v235, v234, v232
	ds_write_b32 v173, v234 offset:14560
	v_mul_f32_e32 v234, 0xbfb8aa3b, v233
	v_exp_f32_e32 v234, v234
	s_nop 0
	v_add_f32_e32 v234, 1.0, v234
	v_div_scale_f32 v235, s[4:5], v234, v234, v233
	v_rcp_f32_e32 v236, v235
	s_nop 0
	v_fma_f32 v237, -v235, v236, 1.0
	v_fmac_f32_e32 v236, v237, v236
	v_div_scale_f32 v237, vcc, v233, v234, v233
	v_mul_f32_e32 v238, v237, v236
	v_fma_f32 v239, -v235, v238, v237
	v_fmac_f32_e32 v238, v239, v236
	v_fma_f32 v235, -v235, v238, v237
	v_div_fmas_f32 v235, v235, v236, v238
	v_div_fixup_f32 v234, v235, v234, v233
	ds_write_b32 v173, v234 offset:15600
	s_waitcnt lgkmcnt(0)
	s_barrier
	s_and_saveexec_b64 s[4:5], s[42:43]
	s_cbranch_execnz .LBB0_343
	s_or_b64 exec, exec, s[4:5]
	s_and_saveexec_b64 s[4:5], s[44:45]
	s_cbranch_execnz .LBB0_344

; DI float bf2f(bf16_t v) { return __uint_as_float(((unsigned)v) << 16); }
; DI float siluf_(float x) { return x / (1.f + __expf(-x)); }
; DI void phase_gdn_prep(const Params& p, int l, char* smem) {
;     ...
;             for (int part = 0; part < 3; ++part) {
; #pragma unroll
;                 for (int k = 0; k < 3; ++k) { const int c = tid + 256 * k; if (c < 67 * 8) *(u32x4*)(sraw + c * 8) = raw[part * 3 + k]; }
;                 __syncthreads();
;                 const int col = part * 384 + h * 64 + ch;
;                 const float w0 = cw[col], w1 = cw[1152 + col], w2 = cw[2 * 1152 + col], w3 = cw[3 * 1152 + col];
;                 float* dst = part == 0 ? sq : (part == 1 ? sk : sv);
; #pragma unroll
;                 for (int i = 0; i < 16; ++i) {
;                     const int t = tq + 4 * i;
;                     const float x0 = bf2f(sraw[(t + 0) * 64 + ch]), x1 = bf2f(sraw[(t + 1) * 64 + ch]);
;                     const float x2 = bf2f(sraw[(t + 2) * 64 + ch]), x3 = bf2f(sraw[(t + 3) * 64 + ch]);
;                     const float a = x0 * w0 + x1 * w1 + x2 * w2 + x3 * w3;
;                     dst[t * 65 + ch] = siluf_(a);
;                 }
;                 __syncthreads();
.LBB0_272:
	s_or_b64 exec, exec, s[4:5]
	v_add_co_u32_e32 v14, vcc, 0x1000, v24
	s_waitcnt lgkmcnt(0)
	s_nop 0
	v_addc_co_u32_e32 v15, vcc, 0, v25, vcc
	s_barrier
	ds_read_u16 v191, v78 offset:49920
	ds_read_u16 v192, v78 offset:50048
	ds_read_u16 v193, v78 offset:50176
	ds_read_u16 v194, v78 offset:50304
	ds_read_u16 v195, v78 offset:50432
	ds_read_u16 v196, v78 offset:50560
	ds_read_u16 v197, v78 offset:50688
	ds_read_u16 v198, v78 offset:50816
	ds_read_u16 v199, v78 offset:50944
	ds_read_u16 v200, v78 offset:51072
	ds_read_u16 v201, v78 offset:51200
	ds_read_u16 v202, v78 offset:51328
	ds_read_u16 v203, v78 offset:51456
	ds_read_u16 v204, v78 offset:51584
	ds_read_u16 v205, v78 offset:51712
	ds_read_u16 v206, v78 offset:51840
	s_waitcnt lgkmcnt(0)
	v_lshlrev_b32_e32 v191, 16, v191
	v_lshlrev_b32_e32 v192, 16, v192
	v_lshlrev_b32_e32 v193, 16, v193
	v_lshlrev_b32_e32 v194, 16, v194
	v_mul_f32_e32 v230, v59, v192
	v_fmac_f32_e32 v230, v58, v191
	v_fmac_f32_e32 v230, v60, v193
	v_fmac_f32_e32 v230, v61, v194
	v_lshlrev_b32_e32 v195, 16, v195
	v_lshlrev_b32_e32 v196, 16, v196
	v_lshlrev_b32_e32 v197, 16, v197
	v_lshlrev_b32_e32 v198, 16, v198
	v_mul_f32_e32 v231, v59, v196
	v_fmac_f32_e32 v231, v58, v195
	v_fmac_f32_e32 v231, v60, v197
	v_fmac_f32_e32 v231, v61, v198
	v_lshlrev_b32_e32 v199, 16, v199
	v_lshlrev_b32_e32 v200, 16, v200
	v_lshlrev_b32_e32 v201, 16, v201
	v_lshlrev_b32_e32 v202, 16, v202
	v_mul_f32_e32 v232, v59, v200
	v_fmac_f32_e32 v232, v58, v199
	v_fmac_f32_e32 v232, v60, v201
	v_fmac_f32_e32 v232, v61, v202
	v_lshlrev_b32_e32 v203, 16, v203
	v_lshlrev_b32_e32 v204, 16, v204
	v_lshlrev_b32_e32 v205, 16, v205
	v_lshlrev_b32_e32 v206, 16, v206
	v_mul_f32_e32 v233, v59, v204
	v_fmac_f32_e32 v233, v58, v203
	v_fmac_f32_e32 v233, v60, v205
	v_fmac_f32_e32 v233, v61, v206
	ds_read_u16 v191, v78 offset:51968
	ds_read_u16 v192, v78 offset:52096
	ds_read_u16 v193, v78 offset:52224
	ds_read_u16 v194, v78 offset:52352
	ds_read_u16 v195, v78 offset:52480
	ds_read_u16 v196, v78 offset:52608
	ds_read_u16 v197, v78 offset:52736
	ds_read_u16 v198, v78 offset:52864
	ds_read_u16 v199, v78 offset:52992
	ds_read_u16 v200, v78 offset:53120
	ds_read_u16 v201, v78 offset:53248
	ds_read_u16 v202, v78 offset:53376
	ds_read_u16 v203, v78 offset:53504
	ds_read_u16 v204, v78 offset:53632
	ds_read_u16 v205, v78 offset:53760
	ds_read_u16 v206, v78 offset:53888
	v_mul_f32_e32 v234, 0xbfb8aa3b, v230
	v_exp_f32_e32 v234, v234
	s_nop 0
	v_add_f32_e32 v234, 1.0, v234
	v_div_scale_f32 v235, s[4:5], v234, v234, v230
	v_rcp_f32_e32 v236, v235
	s_nop 0
	v_fma_f32 v237, -v235, v236, 1.0
	v_fmac_f32_e32 v236, v237, v236
	v_div_scale_f32 v237, vcc, v230, v234, v230
	v_mul_f32_e32 v238, v237, v236
	v_fma_f32 v239, -v235, v238, v237
	v_fmac_f32_e32 v238, v239, v236
	v_fma_f32 v235, -v235, v238, v237
	v_div_fmas_f32 v235, v235, v236, v238
	v_div_fixup_f32 v234, v235, v234, v230
	ds_write_b32 v173, v234 offset:16640
	v_mul_f32_e32 v234, 0xbfb8aa3b, v231
	v_exp_f32_e32 v234, v234
	s_nop 0
	v_add_f32_e32 v234, 1.0, v234
	v_div_scale_f32 v235, s[4:5], v234, v234, v231
	v_rcp_f32_e32 v236, v235
	s_nop 0
	v_fma_f32 v237, -v235, v236, 1.0
	v_fmac_f32_e32 v236, v237, v236
	v_div_scale_f32 v237, vcc, v231, v234, v231
	v_mul_f32_e32 v238, v237, v236
	v_fma_f32 v239, -v235, v238, v237
	v_fmac_f32_e32 v238, v239, v236
	v_fma_f32 v235, -v235, v238, v237
	v_div_fmas_f32 v235, v235, v236, v238
	v_div_fixup_f32 v234, v235, v234, v231
	ds_write_b32 v173, v234 offset:17680
	v_mul_f32_e32 v234, 0xbfb8aa3b, v232
	v_exp_f32_e32 v234, v234
	s_nop 0
	v_add_f32_e32 v234, 1.0, v234
	v_div_scale_f32 v235, s[4:5], v234, v234, v232
	v_rcp_f32_e32 v236, v235
	s_nop 0
	v_fma_f32 v237, -v235, v236, 1.0
	v_fmac_f32_e32 v236, v237, v236
	v_div_scale_f32 v237, vcc, v232, v234, v232
	v_mul_f32_e32 v238, v237, v236
	v_fma_f32 v239, -v235, v238, v237
	v_fmac_f32_e32 v238, v239, v236
	v_fma_f32 v235, -v235, v238, v237
	v_div_fmas_f32 v235, v235, v236, v238
	v_div_fixup_f32 v234, v235, v234, v232
	ds_write_b32 v173, v234 offset:18720
	v_mul_f32_e32 v234, 0xbfb8aa3b, v233
	v_exp_f32_e32 v234, v234
	s_nop 0
	v_add_f32_e32 v234, 1.0, v234
	v_div_scale_f32 v235, s[4:5], v234, v234, v233
	v_rcp_f32_e32 v236, v235
	s_nop 0
	v_fma_f32 v237, -v235, v236, 1.0
	v_fmac_f32_e32 v236, v237, v236
	v_div_scale_f32 v237, vcc, v233, v234, v233
	v_mul_f32_e32 v238, v237, v236
	v_fma_f32 v239, -v235, v238, v237
	v_fmac_f32_e32 v238, v239, v236
	v_fma_f32 v235, -v235, v238, v237
	v_div_fmas_f32 v235, v235, v236, v238
	v_div_fixup_f32 v234, v235, v234, v233
	ds_write_b32 v173, v234 offset:19760
	s_waitcnt lgkmcnt(0)
; DI float bf2f(bf16_t v) { return __uint_as_float(((unsigned)v) << 16); }
; DI float siluf_(float x) { return x / (1.f + __expf(-x)); }
; DI void phase_gdn_prep(const Params& p, int l, char* smem) {
;     ...
; #pragma unroll
;                 for (int i = 0; i < 16; ++i) {
;                     const int t = tq + 4 * i;
;                     const float x0 = bf2f(sraw[(t + 0) * 64 + ch]), x1 = bf2f(sraw[(t + 1) * 64 + ch]);
;                     const float x2 = bf2f(sraw[(t + 2) * 64 + ch]), x3 = bf2f(sraw[(t + 3) * 64 + ch]);
;                     const float a = x0 * w0 + x1 * w1 + x2 * w2 + x3 * w3;
;                     dst[t * 65 + ch] = siluf_(a);
;                 }
;                 __syncthreads();
	v_lshlrev_b32_e32 v191, 16, v191
	v_lshlrev_b32_e32 v192, 16, v192
	v_lshlrev_b32_e32 v193, 16, v193
	v_lshlrev_b32_e32 v194, 16, v194
	v_mul_f32_e32 v230, v59, v192
	v_fmac_f32_e32 v230, v58, v191
	v_fmac_f32_e32 v230, v60, v193
	v_fmac_f32_e32 v230, v61, v194
	v_lshlrev_b32_e32 v195, 16, v195
	v_lshlrev_b32_e32 v196, 16, v196
	v_lshlrev_b32_e32 v197, 16, v197
	v_lshlrev_b32_e32 v198, 16, v198
	v_mul_f32_e32 v231, v59, v196
	v_fmac_f32_e32 v231, v58, v195
	v_fmac_f32_e32 v231, v60, v197
	v_fmac_f32_e32 v231, v61, v198
	v_lshlrev_b32_e32 v199, 16, v199
	v_lshlrev_b32_e32 v200, 16, v200
	v_lshlrev_b32_e32 v201, 16, v201
	v_lshlrev_b32_e32 v202, 16, v202
	v_mul_f32_e32 v232, v59, v200
	v_fmac_f32_e32 v232, v58, v199
	v_fmac_f32_e32 v232, v60, v201
	v_fmac_f32_e32 v232, v61, v202
	v_lshlrev_b32_e32 v203, 16, v203
	v_lshlrev_b32_e32 v204, 16, v204
	v_lshlrev_b32_e32 v205, 16, v205
	v_lshlrev_b32_e32 v206, 16, v206
	v_mul_f32_e32 v233, v59, v204
	v_fmac_f32_e32 v233, v58, v203
	v_fmac_f32_e32 v233, v60, v205
	v_fmac_f32_e32 v233, v61, v206
	ds_read_u16 v191, v78 offset:54016
	ds_read_u16 v192, v78 offset:54144
	ds_read_u16 v193, v78 offset:54272
	ds_read_u16 v194, v78 offset:54400
	ds_read_u16 v195, v78 offset:54528
	ds_read_u16 v196, v78 offset:54656
	ds_read_u16 v197, v78 offset:54784
	ds_read_u16 v198, v78 offset:54912
	ds_read_u16 v199, v78 offset:55040
	ds_read_u16 v200, v78 offset:55168
	ds_read_u16 v201, v78 offset:55296
	ds_read_u16 v202, v78 offset:55424
	ds_read_u16 v203, v78 offset:55552
	ds_read_u16 v204, v78 offset:55680
	ds_read_u16 v205, v78 offset:55808
	ds_read_u16 v206, v78 offset:55936
	v_mul_f32_e32 v234, 0xbfb8aa3b, v230
	v_exp_f32_e32 v234, v234
	s_nop 0
	v_add_f32_e32 v234, 1.0, v234
	v_div_scale_f32 v235, s[4:5], v234, v234, v230
	v_rcp_f32_e32 v236, v235
	s_nop 0
	v_fma_f32 v237, -v235, v236, 1.0
	v_fmac_f32_e32 v236, v237, v236
	v_div_scale_f32 v237, vcc, v230, v234, v230
	v_mul_f32_e32 v238, v237, v236
	v_fma_f32 v239, -v235, v238, v237
	v_fmac_f32_e32 v238, v239, v236
	v_fma_f32 v235, -v235, v238, v237
	v_div_fmas_f32 v235, v235, v236, v238
	v_div_fixup_f32 v234, v235, v234, v230
	ds_write_b32 v173, v234 offset:20800
	v_mul_f32_e32 v234, 0xbfb8aa3b, v231
	v_exp_f32_e32 v234, v234
	s_nop 0
	v_add_f32_e32 v234, 1.0, v234
	v_div_scale_f32 v235, s[4:5], v234, v234, v231
	v_rcp_f32_e32 v236, v235
	s_nop 0
	v_fma_f32 v237, -v235, v236, 1.0
	v_fmac_f32_e32 v236, v237, v236
	v_div_scale_f32 v237, vcc, v231, v234, v231
	v_mul_f32_e32 v238, v237, v236
	v_fma_f32 v239, -v235, v238, v237
	v_fmac_f32_e32 v238, v239, v236
	v_fma_f32 v235, -v235, v238, v237
	v_div_fmas_f32 v235, v235, v236, v238
	v_div_fixup_f32 v234, v235, v234, v231
	ds_write_b32 v173, v234 offset:21840
	v_mul_f32_e32 v234, 0xbfb8aa3b, v232
	v_exp_f32_e32 v234, v234
	s_nop 0
	v_add_f32_e32 v234, 1.0, v234
	v_div_scale_f32 v235, s[4:5], v234, v234, v232
	v_rcp_f32_e32 v236, v235
	s_nop 0
	v_fma_f32 v237, -v235, v236, 1.0
	v_fmac_f32_e32 v236, v237, v236
	v_div_scale_f32 v237, vcc, v232, v234, v232
	v_mul_f32_e32 v238, v237, v236
	v_fma_f32 v239, -v235, v238, v237
	v_fmac_f32_e32 v238, v239, v236
	v_fma_f32 v235, -v235, v238, v237
	v_div_fmas_f32 v235, v235, v236, v238
	v_div_fixup_f32 v234, v235, v234, v232
	ds_write_b32 v173, v234 offset:22880
	v_mul_f32_e32 v234, 0xbfb8aa3b, v233
	v_exp_f32_e32 v234, v234
	s_nop 0
	v_add_f32_e32 v234, 1.0, v234
	v_div_scale_f32 v235, s[4:5], v234, v234, v233
	v_rcp_f32_e32 v236, v235
	s_nop 0
	v_fma_f32 v237, -v235, v236, 1.0
	v_fmac_f32_e32 v236, v237, v236
	v_div_scale_f32 v237, vcc, v233, v234, v233
	v_mul_f32_e32 v238, v237, v236
	v_fma_f32 v239, -v235, v238, v237
	v_fmac_f32_e32 v238, v239, v236
	v_fma_f32 v235, -v235, v238, v237
	v_div_fmas_f32 v235, v235, v236, v238
	v_div_fixup_f32 v234, v235, v234, v233
	ds_write_b32 v173, v234 offset:23920
	s_waitcnt lgkmcnt(0)
	v_lshlrev_b32_e32 v191, 16, v191
	v_lshlrev_b32_e32 v192, 16, v192
	v_lshlrev_b32_e32 v193, 16, v193
	v_lshlrev_b32_e32 v194, 16, v194
	v_mul_f32_e32 v230, v59, v192
	v_fmac_f32_e32 v230, v58, v191
	v_fmac_f32_e32 v230, v60, v193
	v_fmac_f32_e32 v230, v61, v194
	v_lshlrev_b32_e32 v195, 16, v195
	v_lshlrev_b32_e32 v196, 16, v196
	v_lshlrev_b32_e32 v197, 16, v197
	v_lshlrev_b32_e32 v198, 16, v198
	v_mul_f32_e32 v231, v59, v196
	v_fmac_f32_e32 v231, v58, v195
	v_fmac_f32_e32 v231, v60, v197
	v_fmac_f32_e32 v231, v61, v198
	v_lshlrev_b32_e32 v199, 16, v199
	v_lshlrev_b32_e32 v200, 16, v200
	v_lshlrev_b32_e32 v201, 16, v201
	v_lshlrev_b32_e32 v202, 16, v202
	v_mul_f32_e32 v232, v59, v200
	v_fmac_f32_e32 v232, v58, v199
	v_fmac_f32_e32 v232, v60, v201
	v_fmac_f32_e32 v232, v61, v202
	v_lshlrev_b32_e32 v203, 16, v203
	v_lshlrev_b32_e32 v204, 16, v204
	v_lshlrev_b32_e32 v205, 16, v205
	v_lshlrev_b32_e32 v206, 16, v206
	v_mul_f32_e32 v233, v59, v204
	v_fmac_f32_e32 v233, v58, v203
	v_fmac_f32_e32 v233, v60, v205
	v_fmac_f32_e32 v233, v61, v206
	ds_read_u16 v191, v78 offset:56064
	ds_read_u16 v192, v78 offset:56192
	ds_read_u16 v193, v78 offset:56320
	ds_read_u16 v194, v78 offset:56448
	ds_read_u16 v195, v78 offset:56576
	ds_read_u16 v196, v78 offset:56704
	ds_read_u16 v197, v78 offset:56832
	ds_read_u16 v198, v78 offset:56960
	ds_read_u16 v199, v78 offset:57088
	ds_read_u16 v200, v78 offset:57216
	ds_read_u16 v201, v78 offset:57344
	ds_read_u16 v202, v78 offset:57472
	ds_read_u16 v203, v78 offset:57600
	ds_read_u16 v204, v78 offset:57728
	ds_read_u16 v205, v78 offset:57856
	ds_read_u16 v206, v78 offset:57984
	v_mul_f32_e32 v234, 0xbfb8aa3b, v230
	v_exp_f32_e32 v234, v234
	s_nop 0
	v_add_f32_e32 v234, 1.0, v234
; DI float bf2f(bf16_t v) { return __uint_as_float(((unsigned)v) << 16); }
; DI float siluf_(float x) { return x / (1.f + __expf(-x)); }
; DI void phase_gdn_prep(const Params& p, int l, char* smem) {
;     ...
; #pragma unroll
;                 for (int i = 0; i < 16; ++i) {
;                     const int t = tq + 4 * i;
;                     const float x0 = bf2f(sraw[(t + 0) * 64 + ch]), x1 = bf2f(sraw[(t + 1) * 64 + ch]);
;                     const float x2 = bf2f(sraw[(t + 2) * 64 + ch]), x3 = bf2f(sraw[(t + 3) * 64 + ch]);
;                     const float a = x0 * w0 + x1 * w1 + x2 * w2 + x3 * w3;
;                     dst[t * 65 + ch] = siluf_(a);
;                 }
;                 __syncthreads();
	v_div_scale_f32 v235, s[4:5], v234, v234, v230
	v_rcp_f32_e32 v236, v235
	s_nop 0
	v_fma_f32 v237, -v235, v236, 1.0
	v_fmac_f32_e32 v236, v237, v236
	v_div_scale_f32 v237, vcc, v230, v234, v230
	v_mul_f32_e32 v238, v237, v236
	v_fma_f32 v239, -v235, v238, v237
	v_fmac_f32_e32 v238, v239, v236
	v_fma_f32 v235, -v235, v238, v237
	v_div_fmas_f32 v235, v235, v236, v238
	v_div_fixup_f32 v234, v235, v234, v230
	ds_write_b32 v173, v234 offset:24960
	v_mul_f32_e32 v234, 0xbfb8aa3b, v231
	v_exp_f32_e32 v234, v234
	s_nop 0
	v_add_f32_e32 v234, 1.0, v234
	v_div_scale_f32 v235, s[4:5], v234, v234, v231
	v_rcp_f32_e32 v236, v235
	s_nop 0
	v_fma_f32 v237, -v235, v236, 1.0
	v_fmac_f32_e32 v236, v237, v236
	v_div_scale_f32 v237, vcc, v231, v234, v231
	v_mul_f32_e32 v238, v237, v236
	v_fma_f32 v239, -v235, v238, v237
	v_fmac_f32_e32 v238, v239, v236
	v_fma_f32 v235, -v235, v238, v237
	v_div_fmas_f32 v235, v235, v236, v238
	v_div_fixup_f32 v234, v235, v234, v231
	ds_write_b32 v173, v234 offset:26000
	v_mul_f32_e32 v234, 0xbfb8aa3b, v232
	v_exp_f32_e32 v234, v234
	s_nop 0
	v_add_f32_e32 v234, 1.0, v234
	v_div_scale_f32 v235, s[4:5], v234, v234, v232
	v_rcp_f32_e32 v236, v235
	s_nop 0
	v_fma_f32 v237, -v235, v236, 1.0
	v_fmac_f32_e32 v236, v237, v236
	v_div_scale_f32 v237, vcc, v232, v234, v232
	v_mul_f32_e32 v238, v237, v236
	v_fma_f32 v239, -v235, v238, v237
	v_fmac_f32_e32 v238, v239, v236
	v_fma_f32 v235, -v235, v238, v237
	v_div_fmas_f32 v235, v235, v236, v238
	v_div_fixup_f32 v234, v235, v234, v232
	ds_write_b32 v173, v234 offset:27040
	v_mul_f32_e32 v234, 0xbfb8aa3b, v233
	v_exp_f32_e32 v234, v234
	s_nop 0
	v_add_f32_e32 v234, 1.0, v234
	v_div_scale_f32 v235, s[4:5], v234, v234, v233
	v_rcp_f32_e32 v236, v235
	s_nop 0
	v_fma_f32 v237, -v235, v236, 1.0
	v_fmac_f32_e32 v236, v237, v236
	v_div_scale_f32 v237, vcc, v233, v234, v233
	v_mul_f32_e32 v238, v237, v236
	v_fma_f32 v239, -v235, v238, v237
	v_fmac_f32_e32 v238, v239, v236
	v_fma_f32 v235, -v235, v238, v237
	v_div_fmas_f32 v235, v235, v236, v238
	v_div_fixup_f32 v234, v235, v234, v233
	ds_write_b32 v173, v234 offset:28080
	s_waitcnt lgkmcnt(0)
	v_lshlrev_b32_e32 v191, 16, v191
	v_lshlrev_b32_e32 v192, 16, v192
	v_lshlrev_b32_e32 v193, 16, v193
	v_lshlrev_b32_e32 v194, 16, v194
	v_mul_f32_e32 v230, v59, v192
	v_fmac_f32_e32 v230, v58, v191
	v_fmac_f32_e32 v230, v60, v193
	v_fmac_f32_e32 v230, v61, v194
	v_lshlrev_b32_e32 v195, 16, v195
	v_lshlrev_b32_e32 v196, 16, v196
	v_lshlrev_b32_e32 v197, 16, v197
	v_lshlrev_b32_e32 v198, 16, v198
	v_mul_f32_e32 v231, v59, v196
	v_fmac_f32_e32 v231, v58, v195
	v_fmac_f32_e32 v231, v60, v197
	v_fmac_f32_e32 v231, v61, v198
	v_lshlrev_b32_e32 v199, 16, v199
	v_lshlrev_b32_e32 v200, 16, v200
	v_lshlrev_b32_e32 v201, 16, v201
	v_lshlrev_b32_e32 v202, 16, v202
	v_mul_f32_e32 v232, v59, v200
	v_fmac_f32_e32 v232, v58, v199
	v_fmac_f32_e32 v232, v60, v201
	v_fmac_f32_e32 v232, v61, v202
	v_lshlrev_b32_e32 v203, 16, v203
	v_lshlrev_b32_e32 v204, 16, v204
	v_lshlrev_b32_e32 v205, 16, v205
	v_lshlrev_b32_e32 v206, 16, v206
	v_mul_f32_e32 v233, v59, v204
	v_fmac_f32_e32 v233, v58, v203
	v_fmac_f32_e32 v233, v60, v205
	v_fmac_f32_e32 v233, v61, v206
	v_mul_f32_e32 v234, 0xbfb8aa3b, v230
	v_exp_f32_e32 v234, v234
	s_nop 0
	v_add_f32_e32 v234, 1.0, v234
	v_div_scale_f32 v235, s[4:5], v234, v234, v230
	v_rcp_f32_e32 v236, v235
	s_nop 0
	v_fma_f32 v237, -v235, v236, 1.0
	v_fmac_f32_e32 v236, v237, v236
	v_div_scale_f32 v237, vcc, v230, v234, v230
	v_mul_f32_e32 v238, v237, v236
	v_fma_f32 v239, -v235, v238, v237
	v_fmac_f32_e32 v238, v239, v236
	v_fma_f32 v235, -v235, v238, v237
	v_div_fmas_f32 v235, v235, v236, v238
	v_div_fixup_f32 v234, v235, v234, v230
	ds_write_b32 v173, v234 offset:29120
	v_mul_f32_e32 v234, 0xbfb8aa3b, v231
	v_exp_f32_e32 v234, v234
	s_nop 0
	v_add_f32_e32 v234, 1.0, v234
	v_div_scale_f32 v235, s[4:5], v234, v234, v231
	v_rcp_f32_e32 v236, v235
	s_nop 0
	v_fma_f32 v237, -v235, v236, 1.0
	v_fmac_f32_e32 v236, v237, v236
	v_div_scale_f32 v237, vcc, v231, v234, v231
	v_mul_f32_e32 v238, v237, v236
	v_fma_f32 v239, -v235, v238, v237
	v_fmac_f32_e32 v238, v239, v236
	v_fma_f32 v235, -v235, v238, v237
	v_div_fmas_f32 v235, v235, v236, v238
	v_div_fixup_f32 v234, v235, v234, v231
	ds_write_b32 v173, v234 offset:30160
	v_mul_f32_e32 v234, 0xbfb8aa3b, v232
	v_exp_f32_e32 v234, v234
	s_nop 0
	v_add_f32_e32 v234, 1.0, v234
	v_div_scale_f32 v235, s[4:5], v234, v234, v232
	v_rcp_f32_e32 v236, v235
	s_nop 0
	v_fma_f32 v237, -v235, v236, 1.0
	v_fmac_f32_e32 v236, v237, v236
	v_div_scale_f32 v237, vcc, v232, v234, v232
	v_mul_f32_e32 v238, v237, v236
	v_fma_f32 v239, -v235, v238, v237
	v_fmac_f32_e32 v238, v239, v236
	v_fma_f32 v235, -v235, v238, v237
	v_div_fmas_f32 v235, v235, v236, v238
	v_div_fixup_f32 v234, v235, v234, v232
	ds_write_b32 v173, v234 offset:31200
	v_mul_f32_e32 v234, 0xbfb8aa3b, v233
	v_exp_f32_e32 v234, v234
	s_nop 0
	v_add_f32_e32 v234, 1.0, v234
	v_div_scale_f32 v235, s[4:5], v234, v234, v233
	v_rcp_f32_e32 v236, v235
	s_nop 0
	v_fma_f32 v237, -v235, v236, 1.0
	v_fmac_f32_e32 v236, v237, v236
	v_div_scale_f32 v237, vcc, v233, v234, v233
	v_mul_f32_e32 v238, v237, v236
	v_fma_f32 v239, -v235, v238, v237
	v_fmac_f32_e32 v238, v239, v236
	v_fma_f32 v235, -v235, v238, v237
	v_div_fmas_f32 v235, v235, v236, v238
	v_div_fixup_f32 v234, v235, v234, v233
	ds_write_b32 v173, v234 offset:32240
	s_waitcnt lgkmcnt(0)
	s_barrier
	s_and_saveexec_b64 s[4:5], s[42:43]
	s_cbranch_execnz .LBB0_345
	s_or_b64 exec, exec, s[4:5]
	s_and_saveexec_b64 s[4:5], s[44:45]
	s_cbranch_execnz .LBB0_346

; DI float bf2f(bf16_t v) { return __uint_as_float(((unsigned)v) << 16); }
; DI float siluf_(float x) { return x / (1.f + __expf(-x)); }
; DI void phase_gdn_prep(const Params& p, int l, char* smem) {
;     ...
;             for (int part = 0; part < 3; ++part) {
; #pragma unroll
;                 for (int k = 0; k < 3; ++k) { const int c = tid + 256 * k; if (c < 67 * 8) *(u32x4*)(sraw + c * 8) = raw[part * 3 + k]; }
;                 __syncthreads();
;                 const int col = part * 384 + h * 64 + ch;
;                 const float w0 = cw[col], w1 = cw[1152 + col], w2 = cw[2 * 1152 + col], w3 = cw[3 * 1152 + col];
;                 float* dst = part == 0 ? sq : (part == 1 ? sk : sv);
; #pragma unroll
;                 for (int i = 0; i < 16; ++i) {
;                     const int t = tq + 4 * i;
;                     const float x0 = bf2f(sraw[(t + 0) * 64 + ch]), x1 = bf2f(sraw[(t + 1) * 64 + ch]);
;                     const float x2 = bf2f(sraw[(t + 2) * 64 + ch]), x3 = bf2f(sraw[(t + 3) * 64 + ch]);
;                     const float a = x0 * w0 + x1 * w1 + x2 * w2 + x3 * w3;
;                     dst[t * 65 + ch] = siluf_(a);
;                 }
;                 __syncthreads();
.LBB0_276:
	s_or_b64 exec, exec, s[4:5]
	v_add_co_u32_e32 v2, vcc, 0x1000, v24
	s_waitcnt lgkmcnt(0)
	s_nop 0
	v_addc_co_u32_e32 v3, vcc, 0, v25, vcc
	s_barrier
	s_ashr_i32 s87, s86, 31
	ds_read_u16 v191, v78 offset:49920
	ds_read_u16 v192, v78 offset:50048
	ds_read_u16 v193, v78 offset:50176
	ds_read_u16 v194, v78 offset:50304
	ds_read_u16 v195, v78 offset:50432
	ds_read_u16 v196, v78 offset:50560
	ds_read_u16 v197, v78 offset:50688
	ds_read_u16 v198, v78 offset:50816
	ds_read_u16 v199, v78 offset:50944
	ds_read_u16 v200, v78 offset:51072
	ds_read_u16 v201, v78 offset:51200
	ds_read_u16 v202, v78 offset:51328
	ds_read_u16 v203, v78 offset:51456
	ds_read_u16 v204, v78 offset:51584
	ds_read_u16 v205, v78 offset:51712
	ds_read_u16 v206, v78 offset:51840
	s_waitcnt lgkmcnt(0)
	v_lshlrev_b32_e32 v191, 16, v191
	v_lshlrev_b32_e32 v192, 16, v192
	v_lshlrev_b32_e32 v193, 16, v193
	v_lshlrev_b32_e32 v194, 16, v194
	v_mul_f32_e32 v230, v185, v192
	v_fmac_f32_e32 v230, v76, v191
	v_fmac_f32_e32 v230, v186, v193
	v_fmac_f32_e32 v230, v187, v194
	v_lshlrev_b32_e32 v195, 16, v195
	v_lshlrev_b32_e32 v196, 16, v196
	v_lshlrev_b32_e32 v197, 16, v197
	v_lshlrev_b32_e32 v198, 16, v198
	v_mul_f32_e32 v231, v185, v196
	v_fmac_f32_e32 v231, v76, v195
	v_fmac_f32_e32 v231, v186, v197
	v_fmac_f32_e32 v231, v187, v198
	v_lshlrev_b32_e32 v199, 16, v199
	v_lshlrev_b32_e32 v200, 16, v200
	v_lshlrev_b32_e32 v201, 16, v201
	v_lshlrev_b32_e32 v202, 16, v202
	v_mul_f32_e32 v232, v185, v200
	v_fmac_f32_e32 v232, v76, v199
	v_fmac_f32_e32 v232, v186, v201
	v_fmac_f32_e32 v232, v187, v202
	v_lshlrev_b32_e32 v203, 16, v203
	v_lshlrev_b32_e32 v204, 16, v204
	v_lshlrev_b32_e32 v205, 16, v205
	v_lshlrev_b32_e32 v206, 16, v206
	v_mul_f32_e32 v233, v185, v204
	v_fmac_f32_e32 v233, v76, v203
	v_fmac_f32_e32 v233, v186, v205
	v_fmac_f32_e32 v233, v187, v206
	ds_read_u16 v191, v78 offset:51968
	ds_read_u16 v192, v78 offset:52096
	ds_read_u16 v193, v78 offset:52224
	ds_read_u16 v194, v78 offset:52352
	ds_read_u16 v195, v78 offset:52480
	ds_read_u16 v196, v78 offset:52608
	ds_read_u16 v197, v78 offset:52736
	ds_read_u16 v198, v78 offset:52864
	ds_read_u16 v199, v78 offset:52992
	ds_read_u16 v200, v78 offset:53120
	ds_read_u16 v201, v78 offset:53248
	ds_read_u16 v202, v78 offset:53376
	ds_read_u16 v203, v78 offset:53504
	ds_read_u16 v204, v78 offset:53632
	ds_read_u16 v205, v78 offset:53760
	ds_read_u16 v206, v78 offset:53888
	v_mul_f32_e32 v234, 0xbfb8aa3b, v230
	v_exp_f32_e32 v234, v234
	s_nop 0
	v_add_f32_e32 v234, 1.0, v234
	v_div_scale_f32 v235, s[4:5], v234, v234, v230
	v_rcp_f32_e32 v236, v235
	s_nop 0
	v_fma_f32 v237, -v235, v236, 1.0
	v_fmac_f32_e32 v236, v237, v236
	v_div_scale_f32 v237, vcc, v230, v234, v230
	v_mul_f32_e32 v238, v237, v236
	v_fma_f32 v239, -v235, v238, v237
	v_fmac_f32_e32 v238, v239, v236
	v_fma_f32 v235, -v235, v238, v237
	v_div_fmas_f32 v235, v235, v236, v238
	v_div_fixup_f32 v234, v235, v234, v230
	ds_write_b32 v173, v234 offset:33280
	v_mul_f32_e32 v234, 0xbfb8aa3b, v231
	v_exp_f32_e32 v234, v234
	s_nop 0
	v_add_f32_e32 v234, 1.0, v234
	v_div_scale_f32 v235, s[4:5], v234, v234, v231
	v_rcp_f32_e32 v236, v235
	s_nop 0
	v_fma_f32 v237, -v235, v236, 1.0
	v_fmac_f32_e32 v236, v237, v236
	v_div_scale_f32 v237, vcc, v231, v234, v231
	v_mul_f32_e32 v238, v237, v236
	v_fma_f32 v239, -v235, v238, v237
	v_fmac_f32_e32 v238, v239, v236
	v_fma_f32 v235, -v235, v238, v237
	v_div_fmas_f32 v235, v235, v236, v238
	v_div_fixup_f32 v234, v235, v234, v231
	ds_write_b32 v173, v234 offset:34320
	v_mul_f32_e32 v234, 0xbfb8aa3b, v232
	v_exp_f32_e32 v234, v234
	s_nop 0
	v_add_f32_e32 v234, 1.0, v234
	v_div_scale_f32 v235, s[4:5], v234, v234, v232
	v_rcp_f32_e32 v236, v235
	s_nop 0
	v_fma_f32 v237, -v235, v236, 1.0
	v_fmac_f32_e32 v236, v237, v236
	v_div_scale_f32 v237, vcc, v232, v234, v232
	v_mul_f32_e32 v238, v237, v236
	v_fma_f32 v239, -v235, v238, v237
	v_fmac_f32_e32 v238, v239, v236
	v_fma_f32 v235, -v235, v238, v237
	v_div_fmas_f32 v235, v235, v236, v238
	v_div_fixup_f32 v234, v235, v234, v232
	ds_write_b32 v173, v234 offset:35360
	v_mul_f32_e32 v234, 0xbfb8aa3b, v233
	v_exp_f32_e32 v234, v234
	s_nop 0
	v_add_f32_e32 v234, 1.0, v234
	v_div_scale_f32 v235, s[4:5], v234, v234, v233
	v_rcp_f32_e32 v236, v235
	s_nop 0
	v_fma_f32 v237, -v235, v236, 1.0
	v_fmac_f32_e32 v236, v237, v236
	v_div_scale_f32 v237, vcc, v233, v234, v233
	v_mul_f32_e32 v238, v237, v236
	v_fma_f32 v239, -v235, v238, v237
	v_fmac_f32_e32 v238, v239, v236
	v_fma_f32 v235, -v235, v238, v237
	v_div_fmas_f32 v235, v235, v236, v238
	v_div_fixup_f32 v234, v235, v234, v233
	ds_write_b32 v173, v234 offset:36400
	s_waitcnt lgkmcnt(0)
; DI float bf2f(bf16_t v) { return __uint_as_float(((unsigned)v) << 16); }
; DI float siluf_(float x) { return x / (1.f + __expf(-x)); }
; DI void phase_gdn_prep(const Params& p, int l, char* smem) {
;     ...
; #pragma unroll
;                 for (int i = 0; i < 16; ++i) {
;                     const int t = tq + 4 * i;
;                     const float x0 = bf2f(sraw[(t + 0) * 64 + ch]), x1 = bf2f(sraw[(t + 1) * 64 + ch]);
;                     const float x2 = bf2f(sraw[(t + 2) * 64 + ch]), x3 = bf2f(sraw[(t + 3) * 64 + ch]);
;                     const float a = x0 * w0 + x1 * w1 + x2 * w2 + x3 * w3;
;                     dst[t * 65 + ch] = siluf_(a);
;                 }
;                 __syncthreads();
	v_lshlrev_b32_e32 v191, 16, v191
	v_lshlrev_b32_e32 v192, 16, v192
	v_lshlrev_b32_e32 v193, 16, v193
	v_lshlrev_b32_e32 v194, 16, v194
	v_mul_f32_e32 v230, v185, v192
	v_fmac_f32_e32 v230, v76, v191
	v_fmac_f32_e32 v230, v186, v193
	v_fmac_f32_e32 v230, v187, v194
	v_lshlrev_b32_e32 v195, 16, v195
	v_lshlrev_b32_e32 v196, 16, v196
	v_lshlrev_b32_e32 v197, 16, v197
	v_lshlrev_b32_e32 v198, 16, v198
	v_mul_f32_e32 v231, v185, v196
	v_fmac_f32_e32 v231, v76, v195
	v_fmac_f32_e32 v231, v186, v197
	v_fmac_f32_e32 v231, v187, v198
	v_lshlrev_b32_e32 v199, 16, v199
	v_lshlrev_b32_e32 v200, 16, v200
	v_lshlrev_b32_e32 v201, 16, v201
	v_lshlrev_b32_e32 v202, 16, v202
	v_mul_f32_e32 v232, v185, v200
	v_fmac_f32_e32 v232, v76, v199
	v_fmac_f32_e32 v232, v186, v201
	v_fmac_f32_e32 v232, v187, v202
	v_lshlrev_b32_e32 v203, 16, v203
	v_lshlrev_b32_e32 v204, 16, v204
	v_lshlrev_b32_e32 v205, 16, v205
	v_lshlrev_b32_e32 v206, 16, v206
	v_mul_f32_e32 v233, v185, v204
	v_fmac_f32_e32 v233, v76, v203
	v_fmac_f32_e32 v233, v186, v205
	v_fmac_f32_e32 v233, v187, v206
	ds_read_u16 v191, v78 offset:54016
	ds_read_u16 v192, v78 offset:54144
	ds_read_u16 v193, v78 offset:54272
	ds_read_u16 v194, v78 offset:54400
	ds_read_u16 v195, v78 offset:54528
	ds_read_u16 v196, v78 offset:54656
	ds_read_u16 v197, v78 offset:54784
	ds_read_u16 v198, v78 offset:54912
	ds_read_u16 v199, v78 offset:55040
	ds_read_u16 v200, v78 offset:55168
	ds_read_u16 v201, v78 offset:55296
	ds_read_u16 v202, v78 offset:55424
	ds_read_u16 v203, v78 offset:55552
	ds_read_u16 v204, v78 offset:55680
	ds_read_u16 v205, v78 offset:55808
	ds_read_u16 v206, v78 offset:55936
	v_mul_f32_e32 v234, 0xbfb8aa3b, v230
	v_exp_f32_e32 v234, v234
	s_nop 0
	v_add_f32_e32 v234, 1.0, v234
	v_div_scale_f32 v235, s[4:5], v234, v234, v230
	v_rcp_f32_e32 v236, v235
	s_nop 0
	v_fma_f32 v237, -v235, v236, 1.0
	v_fmac_f32_e32 v236, v237, v236
	v_div_scale_f32 v237, vcc, v230, v234, v230
	v_mul_f32_e32 v238, v237, v236
	v_fma_f32 v239, -v235, v238, v237
	v_fmac_f32_e32 v238, v239, v236
	v_fma_f32 v235, -v235, v238, v237
	v_div_fmas_f32 v235, v235, v236, v238
	v_div_fixup_f32 v234, v235, v234, v230
	ds_write_b32 v173, v234 offset:37440
	v_mul_f32_e32 v234, 0xbfb8aa3b, v231
	v_exp_f32_e32 v234, v234
	s_nop 0
	v_add_f32_e32 v234, 1.0, v234
	v_div_scale_f32 v235, s[4:5], v234, v234, v231
	v_rcp_f32_e32 v236, v235
	s_nop 0
	v_fma_f32 v237, -v235, v236, 1.0
	v_fmac_f32_e32 v236, v237, v236
	v_div_scale_f32 v237, vcc, v231, v234, v231
	v_mul_f32_e32 v238, v237, v236
	v_fma_f32 v239, -v235, v238, v237
	v_fmac_f32_e32 v238, v239, v236
	v_fma_f32 v235, -v235, v238, v237
	v_div_fmas_f32 v235, v235, v236, v238
	v_div_fixup_f32 v234, v235, v234, v231
	ds_write_b32 v173, v234 offset:38480
	v_mul_f32_e32 v234, 0xbfb8aa3b, v232
	v_exp_f32_e32 v234, v234
	s_nop 0
	v_add_f32_e32 v234, 1.0, v234
	v_div_scale_f32 v235, s[4:5], v234, v234, v232
	v_rcp_f32_e32 v236, v235
	s_nop 0
	v_fma_f32 v237, -v235, v236, 1.0
	v_fmac_f32_e32 v236, v237, v236
	v_div_scale_f32 v237, vcc, v232, v234, v232
	v_mul_f32_e32 v238, v237, v236
	v_fma_f32 v239, -v235, v238, v237
	v_fmac_f32_e32 v238, v239, v236
	v_fma_f32 v235, -v235, v238, v237
	v_div_fmas_f32 v235, v235, v236, v238
	v_div_fixup_f32 v234, v235, v234, v232
	ds_write_b32 v173, v234 offset:39520
	v_mul_f32_e32 v234, 0xbfb8aa3b, v233
	v_exp_f32_e32 v234, v234
	s_nop 0
	v_add_f32_e32 v234, 1.0, v234
	v_div_scale_f32 v235, s[4:5], v234, v234, v233
	v_rcp_f32_e32 v236, v235
	s_nop 0
	v_fma_f32 v237, -v235, v236, 1.0
	v_fmac_f32_e32 v236, v237, v236
	v_div_scale_f32 v237, vcc, v233, v234, v233
	v_mul_f32_e32 v238, v237, v236
	v_fma_f32 v239, -v235, v238, v237
	v_fmac_f32_e32 v238, v239, v236
	v_fma_f32 v235, -v235, v238, v237
	v_div_fmas_f32 v235, v235, v236, v238
	v_div_fixup_f32 v234, v235, v234, v233
	ds_write_b32 v173, v234 offset:40560
	s_waitcnt lgkmcnt(0)
	v_lshlrev_b32_e32 v191, 16, v191
	v_lshlrev_b32_e32 v192, 16, v192
	v_lshlrev_b32_e32 v193, 16, v193
	v_lshlrev_b32_e32 v194, 16, v194
	v_mul_f32_e32 v230, v185, v192
	v_fmac_f32_e32 v230, v76, v191
	v_fmac_f32_e32 v230, v186, v193
	v_fmac_f32_e32 v230, v187, v194
	v_lshlrev_b32_e32 v195, 16, v195
	v_lshlrev_b32_e32 v196, 16, v196
	v_lshlrev_b32_e32 v197, 16, v197
	v_lshlrev_b32_e32 v198, 16, v198
	v_mul_f32_e32 v231, v185, v196
	v_fmac_f32_e32 v231, v76, v195
	v_fmac_f32_e32 v231, v186, v197
	v_fmac_f32_e32 v231, v187, v198
	v_lshlrev_b32_e32 v199, 16, v199
	v_lshlrev_b32_e32 v200, 16, v200
	v_lshlrev_b32_e32 v201, 16, v201
	v_lshlrev_b32_e32 v202, 16, v202
	v_mul_f32_e32 v232, v185, v200
	v_fmac_f32_e32 v232, v76, v199
	v_fmac_f32_e32 v232, v186, v201
	v_fmac_f32_e32 v232, v187, v202
	v_lshlrev_b32_e32 v203, 16, v203
	v_lshlrev_b32_e32 v204, 16, v204
	v_lshlrev_b32_e32 v205, 16, v205
	v_lshlrev_b32_e32 v206, 16, v206
	v_mul_f32_e32 v233, v185, v204
	v_fmac_f32_e32 v233, v76, v203
	v_fmac_f32_e32 v233, v186, v205
	v_fmac_f32_e32 v233, v187, v206
	ds_read_u16 v191, v78 offset:56064
	ds_read_u16 v192, v78 offset:56192
	ds_read_u16 v193, v78 offset:56320
	ds_read_u16 v194, v78 offset:56448
	ds_read_u16 v195, v78 offset:56576
	ds_read_u16 v196, v78 offset:56704
	ds_read_u16 v197, v78 offset:56832
	ds_read_u16 v198, v78 offset:56960
	ds_read_u16 v199, v78 offset:57088
	ds_read_u16 v200, v78 offset:57216
	ds_read_u16 v201, v78 offset:57344
	ds_read_u16 v202, v78 offset:57472
	ds_read_u16 v203, v78 offset:57600
	ds_read_u16 v204, v78 offset:57728
	ds_read_u16 v205, v78 offset:57856
	ds_read_u16 v206, v78 offset:57984
	v_mul_f32_e32 v234, 0xbfb8aa3b, v230
	v_exp_f32_e32 v234, v234
	s_nop 0
	v_add_f32_e32 v234, 1.0, v234
	v_div_scale_f32 v235, s[4:5], v234, v234, v230
; DI float bf2f(bf16_t v) { return __uint_as_float(((unsigned)v) << 16); }
; DI float siluf_(float x) { return x / (1.f + __expf(-x)); }
; DI void phase_gdn_prep(const Params& p, int l, char* smem) {
;     ...
; #pragma unroll
;                 for (int i = 0; i < 16; ++i) {
;                     const int t = tq + 4 * i;
;                     const float x0 = bf2f(sraw[(t + 0) * 64 + ch]), x1 = bf2f(sraw[(t + 1) * 64 + ch]);
;                     const float x2 = bf2f(sraw[(t + 2) * 64 + ch]), x3 = bf2f(sraw[(t + 3) * 64 + ch]);
;                     const float a = x0 * w0 + x1 * w1 + x2 * w2 + x3 * w3;
;                     dst[t * 65 + ch] = siluf_(a);
;                 }
;                 __syncthreads();
	v_rcp_f32_e32 v236, v235
	s_nop 0
	v_fma_f32 v237, -v235, v236, 1.0
	v_fmac_f32_e32 v236, v237, v236
	v_div_scale_f32 v237, vcc, v230, v234, v230
	v_mul_f32_e32 v238, v237, v236
	v_fma_f32 v239, -v235, v238, v237
	v_fmac_f32_e32 v238, v239, v236
	v_fma_f32 v235, -v235, v238, v237
	v_div_fmas_f32 v235, v235, v236, v238
	v_div_fixup_f32 v234, v235, v234, v230
	ds_write_b32 v173, v234 offset:41600
	v_mul_f32_e32 v234, 0xbfb8aa3b, v231
	v_exp_f32_e32 v234, v234
	s_nop 0
	v_add_f32_e32 v234, 1.0, v234
	v_div_scale_f32 v235, s[4:5], v234, v234, v231
	v_rcp_f32_e32 v236, v235
	s_nop 0
	v_fma_f32 v237, -v235, v236, 1.0
	v_fmac_f32_e32 v236, v237, v236
	v_div_scale_f32 v237, vcc, v231, v234, v231
	v_mul_f32_e32 v238, v237, v236
	v_fma_f32 v239, -v235, v238, v237
	v_fmac_f32_e32 v238, v239, v236
	v_fma_f32 v235, -v235, v238, v237
	v_div_fmas_f32 v235, v235, v236, v238
	v_div_fixup_f32 v234, v235, v234, v231
	ds_write_b32 v173, v234 offset:42640
	v_mul_f32_e32 v234, 0xbfb8aa3b, v232
	v_exp_f32_e32 v234, v234
	s_nop 0
	v_add_f32_e32 v234, 1.0, v234
	v_div_scale_f32 v235, s[4:5], v234, v234, v232
	v_rcp_f32_e32 v236, v235
	s_nop 0
	v_fma_f32 v237, -v235, v236, 1.0
	v_fmac_f32_e32 v236, v237, v236
	v_div_scale_f32 v237, vcc, v232, v234, v232
	v_mul_f32_e32 v238, v237, v236
	v_fma_f32 v239, -v235, v238, v237
	v_fmac_f32_e32 v238, v239, v236
	v_fma_f32 v235, -v235, v238, v237
	v_div_fmas_f32 v235, v235, v236, v238
	v_div_fixup_f32 v234, v235, v234, v232
	ds_write_b32 v173, v234 offset:43680
	v_mul_f32_e32 v234, 0xbfb8aa3b, v233
	v_exp_f32_e32 v234, v234
	s_nop 0
	v_add_f32_e32 v234, 1.0, v234
	v_div_scale_f32 v235, s[4:5], v234, v234, v233
	v_rcp_f32_e32 v236, v235
	s_nop 0
	v_fma_f32 v237, -v235, v236, 1.0
	v_fmac_f32_e32 v236, v237, v236
	v_div_scale_f32 v237, vcc, v233, v234, v233
	v_mul_f32_e32 v238, v237, v236
	v_fma_f32 v239, -v235, v238, v237
	v_fmac_f32_e32 v238, v239, v236
	v_fma_f32 v235, -v235, v238, v237
	v_div_fmas_f32 v235, v235, v236, v238
	v_div_fixup_f32 v234, v235, v234, v233
	ds_write_b32 v173, v234 offset:44720
	s_waitcnt lgkmcnt(0)
	v_lshlrev_b32_e32 v191, 16, v191
	v_lshlrev_b32_e32 v192, 16, v192
	v_lshlrev_b32_e32 v193, 16, v193
	v_lshlrev_b32_e32 v194, 16, v194
	v_mul_f32_e32 v230, v185, v192
	v_fmac_f32_e32 v230, v76, v191
	v_fmac_f32_e32 v230, v186, v193
	v_fmac_f32_e32 v230, v187, v194
	v_lshlrev_b32_e32 v195, 16, v195
	v_lshlrev_b32_e32 v196, 16, v196
	v_lshlrev_b32_e32 v197, 16, v197
	v_lshlrev_b32_e32 v198, 16, v198
	v_mul_f32_e32 v231, v185, v196
	v_fmac_f32_e32 v231, v76, v195
	v_fmac_f32_e32 v231, v186, v197
	v_fmac_f32_e32 v231, v187, v198
	v_lshlrev_b32_e32 v199, 16, v199
	v_lshlrev_b32_e32 v200, 16, v200
	v_lshlrev_b32_e32 v201, 16, v201
	v_lshlrev_b32_e32 v202, 16, v202
	v_mul_f32_e32 v232, v185, v200
	v_fmac_f32_e32 v232, v76, v199
	v_fmac_f32_e32 v232, v186, v201
	v_fmac_f32_e32 v232, v187, v202
	v_lshlrev_b32_e32 v203, 16, v203
	v_lshlrev_b32_e32 v204, 16, v204
	v_lshlrev_b32_e32 v205, 16, v205
	v_lshlrev_b32_e32 v206, 16, v206
	v_mul_f32_e32 v233, v185, v204
	v_fmac_f32_e32 v233, v76, v203
	v_fmac_f32_e32 v233, v186, v205
	v_fmac_f32_e32 v233, v187, v206
	v_mul_f32_e32 v234, 0xbfb8aa3b, v230
	v_exp_f32_e32 v234, v234
	s_nop 0
	v_add_f32_e32 v234, 1.0, v234
	v_div_scale_f32 v235, s[4:5], v234, v234, v230
	v_rcp_f32_e32 v236, v235
	s_nop 0
	v_fma_f32 v237, -v235, v236, 1.0
	v_fmac_f32_e32 v236, v237, v236
	v_div_scale_f32 v237, vcc, v230, v234, v230
	v_mul_f32_e32 v238, v237, v236
	v_fma_f32 v239, -v235, v238, v237
	v_fmac_f32_e32 v238, v239, v236
	v_fma_f32 v235, -v235, v238, v237
	v_div_fmas_f32 v235, v235, v236, v238
	v_div_fixup_f32 v234, v235, v234, v230
	ds_write_b32 v173, v234 offset:45760
	v_mul_f32_e32 v234, 0xbfb8aa3b, v231
	v_exp_f32_e32 v234, v234
	s_nop 0
	v_add_f32_e32 v234, 1.0, v234
	v_div_scale_f32 v235, s[4:5], v234, v234, v231
	v_rcp_f32_e32 v236, v235
	s_nop 0
	v_fma_f32 v237, -v235, v236, 1.0
	v_fmac_f32_e32 v236, v237, v236
	v_div_scale_f32 v237, vcc, v231, v234, v231
	v_mul_f32_e32 v238, v237, v236
	v_fma_f32 v239, -v235, v238, v237
	v_fmac_f32_e32 v238, v239, v236
	v_fma_f32 v235, -v235, v238, v237
	v_div_fmas_f32 v235, v235, v236, v238
	v_div_fixup_f32 v234, v235, v234, v231
	ds_write_b32 v173, v234 offset:46800
	v_mul_f32_e32 v234, 0xbfb8aa3b, v232
	v_exp_f32_e32 v234, v234
	s_nop 0
	v_add_f32_e32 v234, 1.0, v234
	v_div_scale_f32 v235, s[4:5], v234, v234, v232
	v_rcp_f32_e32 v236, v235
	s_nop 0
	v_fma_f32 v237, -v235, v236, 1.0
	v_fmac_f32_e32 v236, v237, v236
	v_div_scale_f32 v237, vcc, v232, v234, v232
	v_mul_f32_e32 v238, v237, v236
	v_fma_f32 v239, -v235, v238, v237
	v_fmac_f32_e32 v238, v239, v236
	v_fma_f32 v235, -v235, v238, v237
	v_div_fmas_f32 v235, v235, v236, v238
	v_div_fixup_f32 v234, v235, v234, v232
	ds_write_b32 v173, v234 offset:47840
	v_mul_f32_e32 v234, 0xbfb8aa3b, v233
	v_exp_f32_e32 v234, v234
	s_nop 0
	v_add_f32_e32 v234, 1.0, v234
	v_div_scale_f32 v235, s[4:5], v234, v234, v233
	v_rcp_f32_e32 v236, v235
	s_nop 0
	v_fma_f32 v237, -v235, v236, 1.0
	v_fmac_f32_e32 v236, v237, v236
	v_div_scale_f32 v237, vcc, v233, v234, v233
	v_mul_f32_e32 v238, v237, v236
	v_fma_f32 v239, -v235, v238, v237
	v_fmac_f32_e32 v238, v239, v236
	v_fma_f32 v235, -v235, v238, v237
	v_div_fmas_f32 v235, v235, v236, v238
	v_div_fixup_f32 v234, v235, v234, v233
	ds_write_b32 v173, v234 offset:48880
	s_waitcnt lgkmcnt(0)
	s_barrier
; DI void phase_gdn_prep(const Params& p, int l, char* smem) {
;     ...
;         const float bb = pbb, aa = paa;
;         if (tid < 64) {
;             const float xx = aa + p.dt_bias[l * 6 + h];
;             const float sp = xx > 20.f ? xx : log1pf(expf(xx));
;             float g = -expf(p.a_log[l * 6 + h]) * sp;
	s_and_saveexec_b64 s[88:89], s[38:39]
	s_cbranch_execz .LBB0_281
	s_mul_i32 s4, s77, 6
	s_add_i32 s4, s6, s4
	s_ashr_i32 s5, s4, 31
	v_readlane_b32 s52, v251, 18
	s_lshl_b64 s[4:5], s[4:5], 2
	v_readlane_b32 s62, v251, 28
	v_readlane_b32 s63, v251, 29
	s_add_u32 s6, s62, s4
	s_addc_u32 s7, s63, s5
	global_load_dword v0, v189, s[6:7]
	s_mov_b32 s6, 0x41a00000
	v_readlane_b32 s53, v251, 19
	v_readlane_b32 s54, v251, 20
	v_readlane_b32 s55, v251, 21
	v_readlane_b32 s56, v251, 22
	v_readlane_b32 s57, v251, 23
	v_readlane_b32 s58, v251, 24
	v_readlane_b32 s59, v251, 25
	v_readlane_b32 s60, v251, 26
	v_readlane_b32 s61, v251, 27
	v_readlane_b32 s64, v251, 30
	v_readlane_b32 s65, v251, 31
	v_readlane_b32 s66, v251, 32
	v_readlane_b32 s67, v251, 33
	s_waitcnt vmcnt(0)
	v_add_f32_e32 v0, v49, v0
	v_cmp_nlt_f32_e32 vcc, s6, v0
	s_and_saveexec_b64 s[6:7], vcc
	s_cbranch_execz .LBB0_279
	v_mul_f32_e32 v1, 0x3fb8aa3b, v0
	v_rndne_f32_e32 v2, v1
	s_mov_b32 s2, 0x3fb8aa3b
	v_sub_f32_e32 v3, v1, v2
	v_fma_f32 v1, v0, s2, -v1
	v_fmac_f32_e32 v1, 0x32a5705f, v0
	v_add_f32_e32 v1, v3, v1
	v_cvt_i32_f32_e32 v2, v2
	v_exp_f32_e32 v1, v1
	s_mov_b32 s2, 0xc2ce8ed0
	v_cmp_ngt_f32_e32 vcc, s2, v0
	s_mov_b32 s2, 0x42b17218
	v_ldexp_f32 v1, v1, v2
	v_cndmask_b32_e32 v1, 0, v1, vcc
	v_cmp_nlt_f32_e32 vcc, s2, v0
	s_mov_b32 s8, 0x3f2aaaab
	s_nop 0
	v_cndmask_b32_e32 v14, v217, v1, vcc
	v_add_f32_e32 v2, 1.0, v14
	v_add_f32_e32 v0, -1.0, v2
	v_sub_f32_e32 v1, v0, v2
	v_add_f32_e32 v1, 1.0, v1
	v_sub_f32_e32 v0, v14, v0
	v_add_f32_e32 v3, v0, v1
	v_frexp_mant_f32_e32 v4, v2
	v_cvt_f64_f32_e32 v[0:1], v2
	v_frexp_exp_i32_f64_e32 v0, v[0:1]
	v_cmp_gt_f32_e32 vcc, s8, v4
	s_mov_b32 s8, 0x3f317218
	s_nop 0
	v_subbrev_co_u32_e32 v8, vcc, 0, v0, vcc
	v_sub_u32_e32 v0, 0, v8
	v_ldexp_f32 v1, v2, v0
	v_add_f32_e32 v2, -1.0, v1
	v_add_f32_e32 v4, 1.0, v1
	v_ldexp_f32 v0, v3, v0
	v_add_f32_e32 v3, 1.0, v2
	v_add_f32_e32 v5, -1.0, v4
	v_sub_f32_e32 v3, v1, v3
	v_sub_f32_e32 v1, v1, v5
	v_add_f32_e32 v3, v0, v3
	v_add_f32_e32 v0, v0, v1
	v_add_f32_e32 v9, v4, v0
	v_rcp_f32_e32 v11, v9
	v_sub_f32_e32 v1, v4, v9
	v_add_f32_e32 v10, v0, v1
	v_add_f32_e32 v1, v2, v3
	v_mul_f32_e32 v13, v1, v11
	v_sub_f32_e32 v0, v2, v1
	v_mul_f32_e32 v2, v9, v13
	v_fma_f32 v4, v13, v9, -v2
	v_fmac_f32_e32 v4, v13, v10
	v_add_f32_e32 v12, v3, v0
	v_add_f32_e32 v0, v2, v4
	v_sub_f32_e32 v3, v1, v0
	v_pk_add_f32 v[6:7], v[0:1], v[2:3] neg_lo:[0,1] neg_hi:[0,1]
	v_mov_b32_e32 v5, v0
	v_pk_add_f32 v[0:1], v[6:7], v[4:5] neg_lo:[0,1] neg_hi:[0,1]
	s_nop 0
	v_add_f32_e32 v1, v12, v1
	v_add_f32_e32 v0, v0, v1
	v_add_f32_e32 v1, v3, v0
	v_mul_f32_e32 v12, v11, v1
	v_mul_f32_e32 v2, v9, v12
	v_fma_f32 v4, v12, v9, -v2
	v_fmac_f32_e32 v4, v12, v10
	v_sub_f32_e32 v3, v3, v1
	v_add_f32_e32 v9, v0, v3
	v_add_f32_e32 v0, v2, v4
	v_sub_f32_e32 v3, v1, v0
	v_pk_add_f32 v[6:7], v[0:1], v[2:3] neg_lo:[0,1] neg_hi:[0,1]
	v_mov_b32_e32 v5, v0
	v_pk_add_f32 v[0:1], v[6:7], v[4:5] neg_lo:[0,1] neg_hi:[0,1]
	s_nop 0
	v_add_f32_e32 v1, v9, v1
	v_add_f32_e32 v0, v0, v1
	v_add_f32_e32 v1, v13, v12
	v_add_f32_e32 v0, v3, v0
	v_sub_f32_e32 v2, v1, v13
	v_mul_f32_e32 v0, v11, v0
	v_sub_f32_e32 v2, v12, v2
	v_add_f32_e32 v2, v2, v0
	v_add_f32_e32 v4, v1, v2
	v_mul_f32_e32 v5, v4, v4
	v_fmamk_f32 v0, v5, 0x3e9b6dac, v214
	v_fmaak_f32 v191, v5, v0, 0x3f2aaada
	v_cvt_f32_i32_e32 v0, v8
	v_sub_f32_e32 v1, v4, v1
	v_sub_f32_e32 v1, v2, v1
	v_ldexp_f32 v6, v1, 1
	v_mul_f32_e32 v1, v4, v5
	v_ldexp_f32 v3, v4, 1
	v_pk_mul_f32 v[4:5], v[0:1], v[190:191]
	s_nop 0
	v_fma_f32 v2, v0, s8, -v4
	v_fmac_f32_e32 v2, 0xb102e308, v0
	v_pk_add_f32 v[0:1], v[4:5], v[2:3]
	s_mov_b32 s8, 0x7f800000
	v_sub_f32_e32 v3, v1, v3
	v_sub_f32_e32 v3, v5, v3
	v_add_f32_e32 v7, v6, v3
	v_mov_b32_e32 v6, v4
	v_pk_add_f32 v[4:5], v[0:1], v[4:5] neg_lo:[0,1] neg_hi:[0,1]
	v_pk_add_f32 v[8:9], v[0:1], v[6:7]
	v_mov_b32_e32 v3, v0
	v_mov_b32_e32 v5, v9
	v_pk_add_f32 v[10:11], v[2:3], v[4:5] neg_lo:[0,1] neg_hi:[0,1]
	v_pk_add_f32 v[2:3], v[2:3], v[4:5]
	v_mov_b32_e32 v6, v7
	v_pk_add_f32 v[4:5], v[2:3], v[0:1] op_sel:[1,0] op_sel_hi:[0,1] neg_lo:[0,1] neg_hi:[0,1]
	v_pk_add_f32 v[12:13], v[8:9], v[4:5] op_sel_hi:[1,0] neg_lo:[0,1] neg_hi:[0,1]
	v_mov_b32_e32 v8, v9
	v_mov_b32_e32 v9, v3
	v_pk_mov_b32 v[4:5], v[0:1], v[4:5] op_sel:[1,0]
	v_mov_b32_e32 v7, v0
	v_pk_add_f32 v[4:5], v[8:9], v[4:5] neg_lo:[0,1] neg_hi:[0,1]
	v_mov_b32_e32 v12, v10
	v_pk_add_f32 v[0:1], v[6:7], v[4:5] neg_lo:[0,1] neg_hi:[0,1]
	v_mov_b32_e32 v11, v3
	v_pk_add_f32 v[4:5], v[12:13], v[0:1]
	v_cmp_neq_f32_e32 vcc, s8, v14
	v_pk_add_f32 v[6:7], v[4:5], v[4:5] op_sel:[0,1] op_sel_hi:[1,0]
	s_mov_b32 s8, 0x33800000
	v_pk_add_f32 v[2:3], v[2:3], v[6:7] op_sel:[1,0] op_sel_hi:[0,1]
	v_mov_b32_e32 v5, v2
	v_pk_add_f32 v[8:9], v[4:5], v[10:11] neg_lo:[0,1] neg_hi:[0,1]
	v_mov_b32_e32 v1, v6
	v_sub_f32_e32 v3, v4, v8
	v_pk_add_f32 v[0:1], v[0:1], v[8:9] neg_lo:[0,1] neg_hi:[0,1]
	v_sub_f32_e32 v3, v10, v3
	v_add_f32_e32 v0, v0, v3
	v_add_f32_e32 v0, v0, v1
	v_add_f32_e32 v0, v2, v0
	v_cndmask_b32_e32 v0, v217, v0, vcc
	v_cmp_lt_f32_e64 vcc, |v14|, s8
	s_nop 1
	v_cndmask_b32_e32 v0, v0, v14, vcc
